# static priority raise (s_setprio 1) for the second wave of each SIMD inside the SEL band loop
# baseline (speedup 1.0000x reference)
; template <bool SEL> ...
;     ...
;     for (int it0 = 0; it0 < n; it0 += 2) {
;         ring_wait_bar(0);
; #pragma unroll
;         for (int pi = 2; pi < 4; ++pi) if (it0 + pi < n) { const unsigned char* blk = KV + (size_t)(jhi - it0 - pi) * SLOTB; dma_block(lds3, (it0 + pi) & 3, wu, blk, soff, blk + 8192, soff); }
.LBB0_2474:
	s_waitcnt vmcnt(0)
	s_add_i32 s46, s8, 2
	s_waitcnt lgkmcnt(0)
	s_barrier
	v_readfirstlane_b32 s98, v198
	s_bitcmp1_b32 s98, 8
	s_cbranch_scc0 .Lsel_noprio
	s_setprio 1
.Lsel_noprio:
	s_cmp_lt_i32 s0, s46
	s_cselect_b64 s[34:35], -1, 0
	s_and_b64 vcc, exec, s[34:35]
	s_cbranch_vccnz .LBB0_2476
	s_sub_i32 s4, s0, s46
	s_lshl_b64 s[6:7], s[4:5], 14
	s_add_u32 s6, s43, s6
	s_addc_u32 s7, s44, s7
	s_lshl_b32 s4, s46, 14
	s_and_b32 s4, s4, 0x8000
	s_add_i32 s4, s4, s95
	s_waitcnt lgkmcnt(2)
	v_lshl_add_u64 v[60:61], s[6:7], 0, v[0:1]
	s_mov_b32 s6, m0
	s_mov_b32 m0, s4
	s_nop 0
	global_load_lds_dwordx4 v[60:61], off
	s_mov_b32 m0, s6
	v_lshl_add_u64 v[60:61], v[60:61], 0, s[62:63]
	s_addk_i32 s4, 0x2000
	s_mov_b32 s6, m0
	s_mov_b32 m0, s4
	s_nop 0
	global_load_lds_dwordx4 v[60:61], off
	s_mov_b32 m0, s6

; #define GATE(br, cg_) fsigmoid(gatev[br][cg_])
; __device__ __forceinline__ void unitA(unsigned char* lds, PG8_LAS unsigned char* lds3, const Args& a, int b, int g, int T) {
;     ...
;         if (rep_ == REP_SEL - 1)
; #pragma unroll
;         for (int cg_ = 0; cg_ < 2; ++cg_) { const float sc = GATE(1, cg_) / quad_sum(l[cg_]);
; #pragma unroll
;             for (int df = 0; df < 4; ++df) stash[(cg_ * 4 + df) * 512 + tid] += o[cg_][df] * sc; }
;     }
;     for (int rep_ = 0; rep_ < REP_WIN; ++rep_) {
;         float m[2] = {-1e30f, -1e30f}, l[2] = {0.f, 0.f}; f32x4 o[2][4];
; #pragma unroll
;         for (int cg_ = 0; cg_ < 2; ++cg_)
; #pragma unroll
;             for (int df = 0; df < 4; ++df) o[cg_][df] = (f32x4){0.f, 0.f, 0.f, 0.f};
;         band_loop<false>(lds, lds3, (const unsigned char*)a.KVW + (size_t)bg * 128 * SLOTB, T, T - 8 > 0 ? T - 8 : 0, T, 512, q, tq, sw, H, farb, m, l, o, wu, soff, r, fq);
.LBB0_2649:
	s_setprio 0
	v_mul_f32_e32 v32, 0xbfb8aa3b, v139
	v_exp_f32_e32 v32, v32
	v_mov_b32_e32 v33, v127
	s_nop 1
	v_permlane16_swap_b32_e32 v127, v33
	v_add_f32_e32 v32, 1.0, v32
	v_rcp_f32_e32 v32, v32
	v_add_f32_e32 v33, v127, v33
	v_mov_b32_e32 v34, v33
	s_nop 1
	v_permlane32_swap_b32_e32 v33, v34
	v_add_f32_e32 v33, v33, v34
	v_div_scale_f32 v34, s[6:7], v33, v33, v32
	v_rcp_f32_e32 v35, v34
	s_add_u32 s34, s73, s42
	s_addc_u32 s35, s74, 0
	v_fma_f32 v36, -v34, v35, 1.0
	v_fmac_f32_e32 v35, v36, v35
	v_div_scale_f32 v36, vcc, v32, v33, v32
	v_mul_f32_e32 v37, v36, v35
	v_fma_f32 v38, -v34, v37, v36
	v_fmac_f32_e32 v37, v38, v35
	v_fma_f32 v34, -v34, v37, v36
	v_div_fmas_f32 v34, v34, v35, v37
	v_div_fixup_f32 v36, v34, v33, v32
	ds_read_b128 v[32:35], v178
	s_waitcnt lgkmcnt(0)
	v_pk_fma_f32 v[34:35], v[58:59], v[36:37], v[34:35] op_sel_hi:[1,0,1]
	v_pk_fma_f32 v[32:33], v[56:57], v[36:37], v[32:33] op_sel_hi:[1,0,1]
	ds_write_b128 v178, v[32:35]
	ds_read_b128 v[32:35], v178 offset:8192
	s_waitcnt lgkmcnt(0)
	v_pk_fma_f32 v[34:35], v[54:55], v[36:37], v[34:35] op_sel_hi:[1,0,1]
	v_pk_fma_f32 v[32:33], v[52:53], v[36:37], v[32:33] op_sel_hi:[1,0,1]
	ds_write_b128 v178, v[32:35] offset:8192
	ds_read_b128 v[32:35], v178 offset:16384
	s_waitcnt lgkmcnt(0)
	v_pk_fma_f32 v[34:35], v[50:51], v[36:37], v[34:35] op_sel_hi:[1,0,1]
	v_pk_fma_f32 v[32:33], v[48:49], v[36:37], v[32:33] op_sel_hi:[1,0,1]
	ds_write_b128 v178, v[32:35] offset:16384
	ds_read_b128 v[32:35], v178 offset:24576
	s_waitcnt lgkmcnt(0)
	v_pk_fma_f32 v[34:35], v[46:47], v[36:37], v[34:35] op_sel_hi:[1,0,1]
	v_pk_fma_f32 v[32:33], v[44:45], v[36:37], v[32:33] op_sel_hi:[1,0,1]
	ds_write_b128 v178, v[32:35] offset:24576
	v_mul_f32_e32 v32, 0xbfb8aa3b, v138
	v_exp_f32_e32 v32, v32
	v_mov_b32_e32 v33, v126
	s_nop 1
	v_permlane16_swap_b32_e32 v126, v33
	v_add_f32_e32 v32, 1.0, v32
	v_rcp_f32_e32 v32, v32
	v_add_f32_e32 v33, v126, v33
	v_mov_b32_e32 v34, v33
	s_nop 1
	v_permlane32_swap_b32_e32 v33, v34
	v_add_f32_e32 v33, v33, v34
	v_div_scale_f32 v34, s[6:7], v33, v33, v32
	v_rcp_f32_e32 v35, v34
	s_nop 0
	v_fma_f32 v36, -v34, v35, 1.0
	v_fmac_f32_e32 v35, v36, v35
	v_div_scale_f32 v36, vcc, v32, v33, v32
	v_mul_f32_e32 v37, v36, v35
	v_fma_f32 v38, -v34, v37, v36
	v_fmac_f32_e32 v37, v38, v35
	v_fma_f32 v34, -v34, v37, v36
	v_div_fmas_f32 v34, v34, v35, v37
	v_div_fixup_f32 v36, v34, v33, v32
	ds_read_b128 v[32:35], v178 offset:32768
	s_and_b64 vcc, exec, s[28:29]
	s_waitcnt lgkmcnt(0)
	v_pk_fma_f32 v[34:35], v[42:43], v[36:37], v[34:35] op_sel_hi:[1,0,1]
	v_pk_fma_f32 v[32:33], v[40:41], v[36:37], v[32:33] op_sel_hi:[1,0,1]
	ds_write_b128 v178, v[32:35] offset:32768
	ds_read_b128 v[32:35], v178 offset:40960
	s_waitcnt lgkmcnt(0)
	v_pk_fma_f32 v[30:31], v[30:31], v[36:37], v[34:35] op_sel_hi:[1,0,1]
	v_pk_fma_f32 v[28:29], v[28:29], v[36:37], v[32:33] op_sel_hi:[1,0,1]
	ds_write_b128 v178, v[28:31] offset:40960
	ds_read_b128 v[28:31], v178 offset:49152
	s_waitcnt lgkmcnt(0)
	v_pk_fma_f32 v[26:27], v[26:27], v[36:37], v[30:31] op_sel_hi:[1,0,1]
	v_pk_fma_f32 v[24:25], v[24:25], v[36:37], v[28:29] op_sel_hi:[1,0,1]
	ds_write_b128 v178, v[24:27] offset:49152
	ds_read_b128 v[24:27], v178 offset:57344
	s_waitcnt lgkmcnt(0)
	v_pk_fma_f32 v[22:23], v[22:23], v[36:37], v[26:27] op_sel_hi:[1,0,1]
	v_pk_fma_f32 v[20:21], v[20:21], v[36:37], v[24:25] op_sel_hi:[1,0,1]
	ds_write_b128 v178, v[20:23] offset:57344
	s_waitcnt lgkmcnt(0)
	s_barrier
	s_cbranch_vccz .LBB0_2652
	s_mov_b32 s1, s5
	s_lshl_b64 s[6:7], s[0:1], 14
	s_add_u32 s6, s34, s6
	s_addc_u32 s7, s35, s7
	v_lshl_add_u64 v[20:21], s[6:7], 0, v[0:1]
	s_mov_b32 s1, m0
	s_mov_b32 m0, s95
	s_nop 0
	global_load_lds_dwordx4 v[20:21], off
	s_mov_b32 m0, s1
	v_lshl_add_u64 v[22:23], v[20:21], 0, s[62:63]
	s_add_i32 s1, s95, 0x2000
	s_mov_b32 s4, m0
	s_mov_b32 m0, s1
	s_nop 0
	global_load_lds_dwordx4 v[22:23], off
	s_mov_b32 m0, s4
	s_andn2_b64 vcc, exec, s[30:31]
	s_cbranch_vccz .LBB0_2653
